# prompt SSM scan loop diet: dead E-row address chains removed (27 instr), GELU gating in packed f32 (same ops, -28 instr); on top of 0x6000 split
# speedup vs baseline: 1.0030x; 1.0030x over previous
.LBB0_86:
	s_and_b32 s0, s24, 0xff
	v_lshl_or_b32 v2, s0, 12, v157
	s_lshl_b32 s2, s0, 6
	global_load_dwordx4 v[94:97], v2, s[12:13]
	global_load_dwordx4 v[90:93], v2, s[12:13] offset:1024
	global_load_dwordx4 v[86:89], v2, s[12:13] offset:2048
	global_load_dwordx4 v[82:85], v2, s[12:13] offset:3072
	global_load_dwordx4 v[74:77], v2, s[14:15]
	global_load_dwordx4 v[78:81], v2, s[14:15] offset:1024
	global_load_dwordx4 v[70:73], v2, s[14:15] offset:2048
	global_load_dwordx4 v[66:69], v2, s[14:15] offset:3072
	v_or_b32_e32 v2, s2, v122
	v_lshlrev_b32_e32 v2, 2, v2
	v_or_b32_e32 v3, 0x80, v2
	s_mov_b32 s3, s37
	global_load_dword v148, v2, s[6:7]
	global_load_dword v158, v2, s[22:23]
	global_load_dword v142, v3, s[6:7]
	global_load_dword v146, v3, s[22:23]
	v_lshl_add_u64 v[2:3], v[126:127], 0, s[2:3]
	s_ashr_i32 s1, s24, 7
	global_load_dwordx4 v[10:13], v[2:3], off
	v_lshl_add_u64 v[2:3], v[128:129], 0, s[2:3]
	s_and_b32 s27, s1, -2
	global_load_dwordx4 v[14:17], v[2:3], off
	v_or_b32_e32 v2, s27, v123
	v_lshlrev_b32_e32 v2, 11, v2
	v_or_b32_e32 v162, v155, v2
	v_or_b32_e32 v136, v151, v2
	v_add_u32_e32 v2, 0xffffe000, v162
	v_ashrrev_i32_e32 v163, 31, v162
	v_cmp_gt_i32_e32 vcc, s26, v162
	v_lshlrev_b64 v[20:21], 2, v[162:163]
	v_lshl_add_u64 v[22:23], s[38:39], 0, v[20:21]
	v_cndmask_b32_e32 v3, 0, v163, vcc
	v_cndmask_b32_e32 v2, v2, v162, vcc
	v_cndmask_b32_e32 v5, v179, v181, vcc
	v_cndmask_b32_e32 v4, v183, v190, vcc
	v_lshlrev_b64 v[2:3], 14, v[2:3]
	v_lshl_add_u64 v[2:3], v[4:5], 0, v[2:3]
	v_lshl_add_u64 v[2:3], v[2:3], 0, s[2:3]
	v_lshl_add_u64 v[6:7], v[2:3], 0, v[124:125]
	v_add_u32_e32 v19, 0xffffe000, v136
	v_ashrrev_i32_e32 v137, 31, v136
	v_cmp_gt_i32_e32 vcc, s26, v136
	global_load_dwordx4 v[2:5], v[6:7], off offset:16
	s_nop 0
	global_load_dwordx4 v[6:9], v[6:7], off
	v_cndmask_b32_e32 v25, v179, v181, vcc
	global_load_dword v178, v[22:23], off
	v_cndmask_b32_e32 v23, 0, v137, vcc
	v_cndmask_b32_e32 v22, v19, v136, vcc
	v_cndmask_b32_e32 v24, v183, v190, vcc
	v_lshlrev_b64 v[22:23], 14, v[22:23]
	v_lshl_add_u64 v[22:23], v[24:25], 0, v[22:23]
	v_lshl_add_u64 v[22:23], v[22:23], 0, s[2:3]
	v_lshl_add_u64 v[22:23], v[22:23], 0, v[134:135]
	global_load_dwordx4 v[102:105], v[22:23], off
	v_lshlrev_b64 v[22:23], 2, v[136:137]
	v_or_b32_e32 v18, 8, v136
	v_lshl_add_u64 v[24:25], s[38:39], 0, v[22:23]
	global_load_dword v156, v[24:25], off
	v_add_u32_e32 v24, 0xffffe008, v136
	v_ashrrev_i32_e32 v19, 31, v18
	v_cmp_gt_i32_e32 vcc, s26, v18
	s_lshl_b32 s1, s0, 4
	s_lshl_b32 s36, s0, 5
	v_cndmask_b32_e32 v25, 0, v19, vcc
	v_cndmask_b32_e32 v24, v24, v18, vcc
	v_cndmask_b32_e32 v27, v179, v181, vcc
	v_cndmask_b32_e32 v26, v183, v190, vcc
	v_lshlrev_b64 v[24:25], 14, v[24:25]
	v_lshl_add_u64 v[24:25], v[26:27], 0, v[24:25]
	v_lshlrev_b64 v[18:19], 2, v[18:19]
	v_lshl_add_u64 v[24:25], v[24:25], 0, s[2:3]
	v_lshl_add_u64 v[26:27], s[38:39], 0, v[18:19]
	v_lshl_add_u64 v[24:25], v[24:25], 0, v[134:135]
	global_load_dword v150, v[26:27], off
	global_load_dwordx4 v[98:101], v[24:25], off
	v_lshl_add_u64 v[138:139], v[130:131], 0, s[36:37]
	v_lshl_add_u64 v[170:171], s[44:45], 0, v[18:19]
	v_lshl_add_u64 v[172:173], s[44:45], 0, v[22:23]
	v_lshl_add_u64 v[174:175], s[44:45], 0, v[20:21]
	s_lshl_b32 s36, s1, 2
	v_mov_b32_e32 v176, v125
	v_mov_b32_e32 v164, v125
	v_mov_b32_e32 v177, v125
	v_mov_b32_e32 v165, v125
	s_waitcnt vmcnt(12)
	v_mov_b32_e32 v149, v148
	s_waitcnt vmcnt(11)
	v_xor_b32_e32 v159, 0x80000000, v158
	v_pk_mov_b32 v[166:167], v[158:159], v[158:159] op_sel:[1,0]
	s_waitcnt vmcnt(9)
	v_xor_b32_e32 v147, 0x80000000, v146
	v_mov_b32_e32 v143, v142
	v_pk_mov_b32 v[168:169], v[146:147], v[146:147] op_sel:[1,0]
	v_mov_b32_e32 v160, v159
	v_mov_b32_e32 v161, v158
	v_mov_b32_e32 v152, v147
	s_waitcnt vmcnt(7)
	v_pk_mul_f32 v[140:141], v[12:13], v[16:17]
	v_pk_mul_f32 v[144:145], v[10:11], v[14:15]
	v_mov_b32_e32 v153, v146
	s_waitcnt vmcnt(0)
	s_mul_i32 s99, s93, 0x7800
	s_add_i32 s99, s99, 0x11000
	s_mov_b32 s98, 0x1400
	s_add_i32 s100, s99, s98
	v_lshlrev_b32_e32 v206, 4, v154
	v_lshlrev_b32_e32 v207, 2, v154
	s_movk_i32 s3, 0xffb0
	v_mov_b32_e32 v236, 0x3d372713
	v_mov_b32_e32 v238, 0x3f4c422a
	v_mov_b32_e32 v242, -2.0
	v_mov_b32_e32 v244, 0x3fb8aa3b
	v_mov_b32_e32 v246, 1.0
	v_and_b32_e32 v218, 7, v154
	v_bfe_u32 v219, v154, 3, 1
	v_lshl_or_b32 v220, v219, 3, v218
	v_add_u32_e32 v219, 2, v219
	v_lshl_or_b32 v221, v219, 3, v218
	v_lshlrev_b32_e32 v212, 2, v220
	v_lshlrev_b32_e32 v213, 2, v221
	v_lshrrev_b32_e32 v218, 4, v154
	v_lshrrev_b32_e32 v219, 1, v218
	v_and_b32_e32 v218, 1, v218
	v_lshlrev_b32_e32 v218, 10, v218
	v_lshl_or_b32 v220, v219, 5, v220
	v_lshl_or_b32 v221, v219, 5, v221
	v_lshl_add_u32 v210, v220, 4, v218
	v_lshl_add_u32 v211, v221, 4, v218
.LBB0_87:
	v_add_u32_e32 v11, s3, v162
	v_add_u32_e32 v184, s3, v136
	v_add_u32_e32 v20, 96, v11
	v_mov_b32_e32 v18, s10
	v_mov_b32_e32 v19, s8
	v_add_u32_e32 v23, 0xffffe060, v11
	v_cmp_gt_i32_e32 vcc, s26, v20
	v_ashrrev_i32_e32 v26, 31, v20
	v_mov_b32_e32 v12, s11
	v_mov_b32_e32 v13, s9
	v_cndmask_b32_e32 v54, v18, v19, vcc
	v_cndmask_b32_e32 v18, v23, v20, vcc
	v_cndmask_b32_e32 v19, 0, v26, vcc
	v_cndmask_b32_e32 v55, v12, v13, vcc
	v_lshlrev_b64 v[62:63], 14, v[18:19]
	v_mov_b64_e32 v[108:109], v[100:101]
	v_lshl_add_u64 v[54:55], v[54:55], 0, v[62:63]
	v_mov_b64_e32 v[112:113], v[104:105]
	v_mov_b64_e32 v[106:107], v[98:99]
	v_mov_b32_e32 v133, v125
	v_lshl_add_u64 v[200:201], v[54:55], 0, s[36:37]
	v_mov_b64_e32 v[110:111], v[102:103]
	v_lshl_add_u64 v[200:201], v[200:201], 0, v[124:125]
	v_mov_b32_e32 v10, v178
	v_mov_b32_e32 v182, v156
	v_mov_b32_e32 v180, v150
	s_add_i32 m0, s100, 0x1000
	s_nop 0
	global_load_lds_dword v[174:175], off
	s_nop 0
	s_nop 0
	s_add_i32 m0, s100, 0x3f0
	s_nop 0
	global_load_lds_dwordx4 v[200:201], off offset:16
	s_add_i32 m0, s100, 0x0
	s_nop 0
	global_load_lds_dwordx4 v[200:201], off
	s_nop 0
	s_nop 0
	s_nop 0
	s_add_i32 s98, s98, 0x1400
	s_cmp_eq_u32 s98, 0x7800
	s_cselect_b32 s98, 0, s98
	s_add_i32 s100, s99, s98
	s_cmp_lt_i32 s3, 0
	s_cbranch_scc1 .Lssm_skip
	v_pk_mul_f32 v[6:7], v[6:7], v[10:11] op_sel_hi:[1,0]
	v_pk_mul_f32 v[8:9], v[8:9], v[10:11] op_sel_hi:[1,0]
	v_pk_mul_f32 v[2:3], v[10:11], v[2:3] op_sel_hi:[0,1]
	v_pk_mul_f32 v[4:5], v[10:11], v[4:5] op_sel_hi:[0,1]
	v_cvt_pk_bf16_f32 v50, v6, v7
	v_cvt_pk_bf16_f32 v51, v8, v9
	v_cvt_pk_bf16_f32 v52, v2, v3
	v_cvt_pk_bf16_f32 v53, v4, v5
	v_mov_b32_e32 v186, v177
	v_mov_b32_e32 v187, v176
	v_mfma_f32_32x32x16_bf16 v[2:17], v[50:53], v[94:97], 0
	v_mov_b32_e32 v188, v165
	v_mov_b32_e32 v189, v164
	v_add_u32_e32 v197, 0x800, v191
	v_add_u32_e32 v196, 0xa00, v191
	v_add_u32_e32 v195, 0x1000, v191
	v_add_u32_e32 v194, 0x1400, v191
	v_add_u32_e32 v163, 0x1800, v191
	v_mfma_f32_32x32x16_bf16 v[34:49], v[50:53], v[90:93], 0
	s_nop 3
	v_mov_b32_e32 v198, v2
	v_mov_b32_e32 v2, v4
	v_mov_b32_e32 v4, v6
	v_mov_b32_e32 v6, v8
	v_add_u32_e32 v193, 0x1a00, v191
	v_add_u32_e32 v137, 0x1c00, v191
	s_nop 1
	v_mov_b32_e32 v199, v34
	v_mfma_f32_32x32x16_bf16 v[18:33], v[50:53], v[86:89], 0
	v_mov_b32_e32 v34, v3
	v_mov_b32_e32 v3, v36
	v_mov_b32_e32 v36, v5
	v_mov_b32_e32 v5, v38
	v_mov_b32_e32 v38, v7
	v_mov_b32_e32 v7, v40
	v_mov_b32_e32 v8, v41
	v_mfma_f32_32x32x16_bf16 v[50:65], v[50:53], v[82:85], 0
	v_mov_b32_e32 v40, v10
	v_mov_b32_e32 v41, v42
	v_mov_b32_e32 v10, v43
	v_mov_b32_e32 v42, v12
	v_mov_b32_e32 v43, v44
	v_mov_b32_e32 v12, v45
	v_mov_b32_e32 v44, v14
	v_mov_b32_e32 v45, v46
	v_mov_b32_e32 v14, v47
	v_mov_b32_e32 v46, v16
	v_mov_b32_e32 v47, v48
	v_mov_b32_e32 v16, v49
	v_mov_b32_e32 v48, v18
	v_mov_b32_e32 v49, v50
	v_mov_b32_e32 v50, v19
	v_mov_b32_e32 v18, v20
	v_mov_b32_e32 v19, v52
	v_mov_b32_e32 v52, v21
	v_mov_b32_e32 v20, v22
	v_mov_b32_e32 v21, v54
	v_mov_b32_e32 v54, v23
	v_mov_b32_e32 v22, v24
	v_mov_b32_e32 v23, v56
	v_mov_b32_e32 v24, v57
	v_mov_b32_e32 v56, v26
	v_mov_b32_e32 v57, v58
	v_mov_b32_e32 v26, v59
	v_mov_b32_e32 v58, v28
	v_mov_b32_e32 v59, v60
	v_mov_b32_e32 v28, v61
	v_mov_b32_e32 v60, v30
	v_mov_b32_e32 v61, v62
	v_mov_b32_e32 v30, v63
	v_mov_b32_e32 v62, v32
	v_mov_b32_e32 v63, v64
	v_mov_b32_e32 v32, v65
	v_pk_fma_f32 v[64:65], v[148:149], v[176:177], v[198:199]
	v_pk_fma_f32 v[48:49], v[142:143], v[164:165], v[48:49]
	v_pk_fma_f32 v[64:65], v[160:161], v[186:187], v[64:65]
	v_pk_fma_f32 v[48:49], v[152:153], v[188:189], v[48:49]
	v_pk_fma_f32 v[34:35], v[148:149], v[64:65], v[34:35]
	v_pk_fma_f32 v[50:51], v[142:143], v[48:49], v[50:51]
	v_cvt_pk_bf16_f32 v164, v48, v49
	v_pk_fma_f32 v[34:35], v[160:161], v[64:65], v[34:35] op_sel:[0,1,0] op_sel_hi:[1,0,1]
	v_pk_fma_f32 v[48:49], v[152:153], v[48:49], v[50:51] op_sel:[0,1,0] op_sel_hi:[1,0,1]
	v_pk_fma_f32 v[2:3], v[148:149], v[34:35], v[2:3]
	v_pk_fma_f32 v[18:19], v[142:143], v[48:49], v[18:19]
	v_pk_fma_f32 v[2:3], v[160:161], v[34:35], v[2:3] op_sel:[0,1,0] op_sel_hi:[1,0,1]
	v_pk_fma_f32 v[18:19], v[152:153], v[48:49], v[18:19] op_sel:[0,1,0] op_sel_hi:[1,0,1]
	v_cvt_pk_bf16_f32 v50, v34, v35
	v_pk_fma_f32 v[34:35], v[148:149], v[2:3], v[36:37]
	v_pk_fma_f32 v[36:37], v[142:143], v[18:19], v[52:53]
	v_cvt_pk_bf16_f32 v51, v48, v49
	v_cvt_pk_bf16_f32 v48, v2, v3
	v_cvt_pk_bf16_f32 v49, v18, v19
	v_pk_fma_f32 v[2:3], v[160:161], v[2:3], v[34:35] op_sel:[0,1,0] op_sel_hi:[1,0,1]
	v_pk_fma_f32 v[18:19], v[152:153], v[18:19], v[36:37] op_sel:[0,1,0] op_sel_hi:[1,0,1]
	v_pk_fma_f32 v[4:5], v[148:149], v[2:3], v[4:5]
	v_pk_fma_f32 v[20:21], v[142:143], v[18:19], v[20:21]
	v_cvt_pk_bf16_f32 v34, v2, v3
	v_pk_fma_f32 v[2:3], v[160:161], v[2:3], v[4:5] op_sel:[0,1,0] op_sel_hi:[1,0,1]
	v_pk_fma_f32 v[4:5], v[152:153], v[18:19], v[20:21] op_sel:[0,1,0] op_sel_hi:[1,0,1]
	v_cvt_pk_bf16_f32 v35, v18, v19
	v_pk_fma_f32 v[18:19], v[148:149], v[2:3], v[38:39]
	v_pk_fma_f32 v[20:21], v[142:143], v[4:5], v[54:55]
	ds_write2_b32 v191, v34, v35 offset0:204 offset1:236
	v_cvt_pk_bf16_f32 v34, v2, v3
	v_cvt_pk_bf16_f32 v35, v4, v5
	v_pk_fma_f32 v[2:3], v[160:161], v[2:3], v[18:19] op_sel:[0,1,0] op_sel_hi:[1,0,1]
	v_pk_fma_f32 v[4:5], v[152:153], v[4:5], v[20:21] op_sel:[0,1,0] op_sel_hi:[1,0,1]
	v_pk_fma_f32 v[6:7], v[148:149], v[2:3], v[6:7]
	v_pk_fma_f32 v[18:19], v[142:143], v[4:5], v[22:23]
	v_cvt_pk_bf16_f32 v20, v2, v3
	v_cvt_pk_bf16_f32 v21, v4, v5
	v_pk_fma_f32 v[2:3], v[158:159], v[2:3], v[6:7] op_sel:[0,0,1] op_sel_hi:[1,1,0]
	v_pk_fma_f32 v[4:5], v[146:147], v[4:5], v[18:19] op_sel:[0,0,1] op_sel_hi:[1,1,0]
	ds_write2_b32 v197, v20, v21 offset0:100 offset1:132
	v_pk_mov_b32 v[6:7], v[2:3], v[2:3] op_sel:[1,0]
	v_pk_fma_f32 v[8:9], v[148:149], v[2:3], v[8:9]
	v_pk_mov_b32 v[18:19], v[4:5], v[4:5] op_sel:[1,0]
	v_pk_fma_f32 v[20:21], v[142:143], v[4:5], v[24:25]
	v_cvt_pk_bf16_f32 v22, v6, v7
	v_pk_fma_f32 v[2:3], v[166:167], v[2:3], v[8:9] op_sel:[0,0,1] op_sel_hi:[1,1,0]
	v_cvt_pk_bf16_f32 v8, v18, v19
	v_pk_fma_f32 v[4:5], v[168:169], v[4:5], v[20:21] op_sel:[0,0,1] op_sel_hi:[1,1,0]
	v_pk_fma_f32 v[6:7], v[148:149], v[2:3], v[40:41]
	ds_write2_b32 v197, v22, v8 offset0:168 offset1:200
	v_pk_fma_f32 v[8:9], v[142:143], v[4:5], v[56:57]
	v_cvt_pk_bf16_f32 v18, v2, v3
	v_cvt_pk_bf16_f32 v19, v4, v5
	v_pk_fma_f32 v[2:3], v[158:159], v[2:3], v[6:7] op_sel:[0,0,1] op_sel_hi:[1,1,0]
	v_pk_fma_f32 v[4:5], v[146:147], v[4:5], v[8:9] op_sel:[0,0,1] op_sel_hi:[1,1,0]
	ds_write2_b32 v196, v18, v19 offset0:108 offset1:140
	v_pk_mov_b32 v[6:7], v[2:3], v[2:3] op_sel:[1,0]
	v_pk_fma_f32 v[8:9], v[148:149], v[2:3], v[10:11]
	v_pk_mov_b32 v[10:11], v[4:5], v[4:5] op_sel:[1,0]
	v_pk_fma_f32 v[18:19], v[142:143], v[4:5], v[26:27]
	v_cvt_pk_bf16_f32 v20, v6, v7
	v_pk_fma_f32 v[2:3], v[166:167], v[2:3], v[8:9] op_sel:[0,0,1] op_sel_hi:[1,1,0]
	v_cvt_pk_bf16_f32 v8, v10, v11
	v_pk_fma_f32 v[4:5], v[168:169], v[4:5], v[18:19] op_sel:[0,0,1] op_sel_hi:[1,1,0]
	v_pk_fma_f32 v[6:7], v[148:149], v[2:3], v[42:43]
	ds_write2_b32 v195, v20, v8 offset0:64 offset1:96
	v_pk_fma_f32 v[8:9], v[142:143], v[4:5], v[58:59]
	v_cvt_pk_bf16_f32 v10, v2, v3
	v_cvt_pk_bf16_f32 v11, v4, v5
	v_pk_fma_f32 v[2:3], v[158:159], v[2:3], v[6:7] op_sel:[0,0,1] op_sel_hi:[1,1,0]
	v_pk_fma_f32 v[4:5], v[146:147], v[4:5], v[8:9] op_sel:[0,0,1] op_sel_hi:[1,1,0]
	ds_write2_b32 v195, v10, v11 offset0:132 offset1:164
	v_pk_mov_b32 v[6:7], v[2:3], v[2:3] op_sel:[1,0]
	v_pk_fma_f32 v[8:9], v[148:149], v[2:3], v[12:13]
	v_pk_mov_b32 v[10:11], v[4:5], v[4:5] op_sel:[1,0]
	v_pk_fma_f32 v[12:13], v[142:143], v[4:5], v[28:29]
	v_cvt_pk_bf16_f32 v18, v6, v7
	v_pk_fma_f32 v[2:3], v[166:167], v[2:3], v[8:9] op_sel:[0,0,1] op_sel_hi:[1,1,0]
	v_cvt_pk_bf16_f32 v8, v10, v11
	v_pk_fma_f32 v[4:5], v[168:169], v[4:5], v[12:13] op_sel:[0,0,1] op_sel_hi:[1,1,0]
	v_pk_fma_f32 v[6:7], v[148:149], v[2:3], v[44:45]
	ds_write2_b32 v195, v18, v8 offset0:200 offset1:232
	v_pk_fma_f32 v[8:9], v[142:143], v[4:5], v[60:61]
	v_cvt_pk_bf16_f32 v10, v2, v3
	v_cvt_pk_bf16_f32 v11, v4, v5
	v_pk_fma_f32 v[2:3], v[158:159], v[2:3], v[6:7] op_sel:[0,0,1] op_sel_hi:[1,1,0]
	v_pk_fma_f32 v[4:5], v[146:147], v[4:5], v[8:9] op_sel:[0,0,1] op_sel_hi:[1,1,0]
	ds_write2_b32 v194, v10, v11 offset0:12 offset1:44
	v_pk_mov_b32 v[6:7], v[2:3], v[2:3] op_sel:[1,0]
	v_pk_fma_f32 v[8:9], v[148:149], v[2:3], v[14:15]
	v_pk_mov_b32 v[10:11], v[4:5], v[4:5] op_sel:[1,0]
	v_pk_fma_f32 v[12:13], v[142:143], v[4:5], v[30:31]
	v_cvt_pk_bf16_f32 v14, v6, v7
	v_pk_fma_f32 v[2:3], v[166:167], v[2:3], v[8:9] op_sel:[0,0,1] op_sel_hi:[1,1,0]
	v_cvt_pk_bf16_f32 v8, v10, v11
	v_pk_fma_f32 v[4:5], v[168:169], v[4:5], v[12:13] op_sel:[0,0,1] op_sel_hi:[1,1,0]
	v_pk_fma_f32 v[6:7], v[148:149], v[2:3], v[46:47]
	ds_write2_b32 v163, v14, v8 offset0:96 offset1:128
	v_pk_fma_f32 v[8:9], v[142:143], v[4:5], v[62:63]
	v_cvt_pk_bf16_f32 v10, v2, v3
	v_cvt_pk_bf16_f32 v11, v4, v5
	v_pk_fma_f32 v[2:3], v[158:159], v[2:3], v[6:7] op_sel:[0,0,1] op_sel_hi:[1,1,0]
	v_pk_fma_f32 v[4:5], v[146:147], v[4:5], v[8:9] op_sel:[0,0,1] op_sel_hi:[1,1,0]
	v_cvt_pk_bf16_f32 v133, v64, v65
	ds_write2_b32 v163, v10, v11 offset0:164 offset1:196
	v_pk_mov_b32 v[6:7], v[2:3], v[2:3] op_sel:[1,0]
	v_pk_fma_f32 v[8:9], v[148:149], v[2:3], v[16:17]
	v_pk_mov_b32 v[10:11], v[4:5], v[4:5] op_sel:[1,0]
	v_pk_fma_f32 v[12:13], v[142:143], v[4:5], v[32:33]
	ds_write2_b32 v191, v133, v164 offset1:32
	v_cvt_pk_bf16_f32 v6, v6, v7
	v_pk_fma_f32 v[176:177], v[166:167], v[2:3], v[8:9] op_sel:[0,0,1] op_sel_hi:[1,1,0]
	v_cvt_pk_bf16_f32 v2, v10, v11
	v_pk_fma_f32 v[164:165], v[168:169], v[4:5], v[12:13] op_sel:[0,0,1] op_sel_hi:[1,1,0]
	v_cvt_pk_bf16_f32 v3, v176, v177
	ds_write2_b32 v193, v6, v2 offset0:104 offset1:136
	v_cvt_pk_bf16_f32 v2, v164, v165
	ds_write2_b32 v191, v50, v51 offset0:68 offset1:100
	ds_write2_b32 v191, v48, v49 offset0:136 offset1:168
	ds_write2_b32 v197, v34, v35 offset0:32 offset1:64
	ds_write2_b32 v137, v3, v2 offset0:44 offset1:76
	s_waitcnt lgkmcnt(0)
	ds_read_b128 v[18:21], v192
	ds_read_b128 v[22:25], v192 offset:4352
	ds_read_b128 v[26:29], v192 offset:64
	ds_read_b128 v[30:33], v192 offset:4416
	ds_read_b128 v[34:37], v192 offset:128
	ds_read_b128 v[38:41], v192 offset:4480
	ds_read_b128 v[42:45], v192 offset:192
	ds_read_b128 v[46:49], v192 offset:4544
	s_waitcnt lgkmcnt(6)
	v_mfma_f32_16x16x32_bf16 v[2:5], v[74:77], v[18:21], 0
	v_mfma_f32_16x16x32_bf16 v[6:9], v[74:77], v[22:25], 0
	s_waitcnt lgkmcnt(4)
	v_mfma_f32_16x16x32_bf16 v[2:5], v[78:81], v[26:29], v[2:5]
	v_mfma_f32_16x16x32_bf16 v[6:9], v[78:81], v[30:33], v[6:9]
	s_waitcnt lgkmcnt(2)
	v_mfma_f32_16x16x32_bf16 v[2:5], v[70:73], v[34:37], v[2:5]
	v_mfma_f32_16x16x32_bf16 v[6:9], v[70:73], v[38:41], v[6:9]
	s_waitcnt lgkmcnt(0)
	v_mfma_f32_16x16x32_bf16 v[2:5], v[66:69], v[42:45], v[2:5]
	v_mfma_f32_16x16x32_bf16 v[6:9], v[66:69], v[46:49], v[6:9]
	s_waitcnt vmcnt(15)
	v_add_u32_e32 v208, s100, v206
	v_add_u32_e32 v209, s100, v207
	v_add_u32_e32 v214, s100, v210
	v_add_u32_e32 v215, s100, v211
	v_add_u32_e32 v216, s100, v212
	v_add_u32_e32 v217, s100, v213
	ds_read_b128 v[118:121], v208
	ds_read_b128 v[114:117], v208 offset:1024
	ds_read_b128 v[102:105], v214
	ds_read_b128 v[98:101], v215
	ds_read_b32 v178, v209 offset:4096
	ds_read_b32 v156, v216 offset:4096
	ds_read_b32 v150, v217 offset:4096
	v_mul_f32_e64 v10, v110, v182
	v_mul_f32_e64 v11, v111, v182
	v_pk_mul_f32 v[12:13], v[112:113], v[182:183] op_sel_hi:[1,0]
	v_pk_fma_f32 v[2:3], v[144:145], v[10:11], v[2:3]
	v_pk_fma_f32 v[4:5], v[140:141], v[12:13], v[4:5]
	v_pk_mul_f32 v[10:11], v[2:3], v[236:237] op_sel_hi:[1,0]
	v_pk_mul_f32 v[12:13], v[4:5], v[236:237] op_sel_hi:[1,0]
	v_pk_mul_f32 v[10:11], v[2:3], v[10:11]
	v_pk_mul_f32 v[12:13], v[4:5], v[12:13]
	v_pk_fma_f32 v[10:11], v[2:3], v[10:11], v[2:3]
	v_pk_fma_f32 v[12:13], v[4:5], v[12:13], v[4:5]
	v_pk_mul_f32 v[10:11], v[10:11], v[238:239] op_sel_hi:[1,0]
	v_pk_mul_f32 v[12:13], v[12:13], v[238:239] op_sel_hi:[1,0]
	v_pk_mul_f32 v[10:11], v[10:11], v[242:243] op_sel_hi:[1,0]
	v_pk_mul_f32 v[12:13], v[12:13], v[242:243] op_sel_hi:[1,0]
	v_pk_mul_f32 v[10:11], v[10:11], v[244:245] op_sel_hi:[1,0]
	v_pk_mul_f32 v[12:13], v[12:13], v[244:245] op_sel_hi:[1,0]
	v_exp_f32_e32 v10, v10
	v_exp_f32_e32 v11, v11
	v_exp_f32_e32 v12, v12
	v_exp_f32_e32 v13, v13
	v_pk_add_f32 v[10:11], v[10:11], v[246:247] op_sel_hi:[1,0]
	v_pk_add_f32 v[12:13], v[12:13], v[246:247] op_sel_hi:[1,0]
	v_rcp_f32_e32 v10, v10
	v_rcp_f32_e32 v11, v11
	v_rcp_f32_e32 v12, v12
	v_rcp_f32_e32 v13, v13
	v_ashrrev_i32_e32 v185, 31, v184
	v_pk_mul_f32 v[2:3], v[2:3], v[10:11]
	s_add_i32 s3, s3, 16
	v_pk_mul_f32 v[4:5], v[4:5], v[12:13]
	v_cvt_pk_bf16_f32 v2, v2, v3
	v_cvt_pk_bf16_f32 v3, v4, v5
	v_pk_mul_f32 v[4:5], v[106:107], v[180:181] op_sel_hi:[1,0]
	v_pk_mul_f32 v[12:13], v[108:109], v[180:181] op_sel_hi:[1,0]
	v_pk_fma_f32 v[4:5], v[144:145], v[4:5], v[6:7]
	v_pk_fma_f32 v[8:9], v[140:141], v[12:13], v[8:9]
	v_lshlrev_b64 v[6:7], 13, v[184:185]
	v_lshl_add_u64 v[6:7], v[138:139], 0, v[6:7]
	global_store_dwordx2 v[6:7], v[2:3], off
	v_pk_mul_f32 v[10:11], v[4:5], v[236:237] op_sel_hi:[1,0]
	v_pk_mul_f32 v[12:13], v[8:9], v[236:237] op_sel_hi:[1,0]
	v_pk_mul_f32 v[10:11], v[4:5], v[10:11]
	v_pk_mul_f32 v[12:13], v[8:9], v[12:13]
	v_pk_fma_f32 v[10:11], v[4:5], v[10:11], v[4:5]
	v_pk_fma_f32 v[12:13], v[8:9], v[12:13], v[8:9]
	v_pk_mul_f32 v[10:11], v[10:11], v[238:239] op_sel_hi:[1,0]
	v_pk_mul_f32 v[12:13], v[12:13], v[238:239] op_sel_hi:[1,0]
	v_pk_mul_f32 v[10:11], v[10:11], v[242:243] op_sel_hi:[1,0]
	v_pk_mul_f32 v[12:13], v[12:13], v[242:243] op_sel_hi:[1,0]
	v_pk_mul_f32 v[10:11], v[10:11], v[244:245] op_sel_hi:[1,0]
	v_pk_mul_f32 v[12:13], v[12:13], v[244:245] op_sel_hi:[1,0]
	v_exp_f32_e32 v10, v10
	v_exp_f32_e32 v11, v11
	v_exp_f32_e32 v12, v12
	v_exp_f32_e32 v13, v13
	v_pk_add_f32 v[10:11], v[10:11], v[246:247] op_sel_hi:[1,0]
	v_pk_add_f32 v[12:13], v[12:13], v[246:247] op_sel_hi:[1,0]
	v_rcp_f32_e32 v10, v10
	v_rcp_f32_e32 v11, v11
	v_rcp_f32_e32 v12, v12
	v_rcp_f32_e32 v13, v13
	v_add_u32_e32 v6, 8, v184
	v_pk_mul_f32 v[2:3], v[4:5], v[10:11]
	v_pk_mul_f32 v[4:5], v[8:9], v[12:13]
	v_ashrrev_i32_e32 v7, 31, v6
	v_cvt_pk_bf16_f32 v2, v2, v3
	v_cvt_pk_bf16_f32 v3, v4, v5
	v_lshlrev_b64 v[4:5], 13, v[6:7]
	v_lshl_add_u64 v[4:5], v[138:139], 0, v[4:5]
	global_store_dwordx2 v[4:5], v[2:3], off
	s_waitcnt lgkmcnt(0)
	v_mov_b64_e32 v[6:7], v[118:119]
	v_mov_b64_e32 v[2:3], v[114:115]
	v_lshl_add_u64 v[170:171], v[170:171], 0, 64
	v_lshl_add_u64 v[172:173], v[172:173], 0, 64
	v_lshl_add_u64 v[174:175], v[174:175], 0, 64
	s_cmpk_lg_i32 s3, 0x7f0
	v_mov_b64_e32 v[8:9], v[120:121]
	v_mov_b64_e32 v[4:5], v[116:117]
	s_cbranch_scc1 .LBB0_87
	s_branch .Lssm_after
